# mixer A tile loop head aligned to 64 B (was 24 mod 64); shifts all later code
# baseline (speedup 1.0000x reference)
; #define LAS __attribute__((address_space(3)))
; DI size_t zrowU(int row0, int NT) { return ((size_t)((row0 >> 8) * NT) << 16) + (size_t)((((row0 >> 7) & 1) << 15) | (((row0 >> 5) & 1) << 14) | (((row0 >> 6) & 1) << 11)); }
; DI unsigned zlaneRC(int r5, int col) { return (unsigned)(((col >> 8) << 16) | ((r5 >> 4) << 13) | (((col >> 7) & 1) << 12) | (((col >> 5) & 3) << 9) | (((col >> 3) & 3) << 7) | ((r5 & 15) << 3) | (col & 7)); }
; DI void attnA_item(bf16_t* z, const float* sinks, int hp, int qs, LAS bf16_t* vs, const LAS float* btab, int lane) {
;     ...
;     const int qrow0 = metaq ? SEQ : 32 * qs;
;     LAS bf16x8* qs_lds = (LAS bf16x8*)(vs + 32 * PA) + lane;
;     { bf16x8 qf[2][4];
; #pragma unroll
;       for (int u = 0; u < 2; ++u) { const bf16_t* qp = z + zrowU(qrow0, 18) + zlaneRC(c, (2 * hp + u) * 64 + 8 * h);
; #pragma unroll
;         for (int s = 0; s < 4; ++s) qf[u][s] = *(const bf16x8*)(qp + (((s >> 1) << 9) | ((s & 1) << 8))); }
;       asm volatile("s_waitcnt lgkmcnt(0)" ::: "memory");
; #pragma unroll
;       for (int u = 0; u < 2; ++u)
; #pragma unroll
;         for (int s = 0; s < 4; ++s) qs_lds[64 * (4 * u + s)] = qf[u][s]; }
;     f32x16 acc[2][2];
; #pragma unroll
;     for (int u = 0; u < 2; ++u)
; #pragma unroll
;         for (int dt = 0; dt < 2; ++dt)
; #pragma unroll
;             for (int i = 0; i < 16; ++i) acc[u][dt][i] = 0.f;
;     float m[2] = {sinks[2 * hp] * 1.4426950408889634f, sinks[2 * hp + 1] * 1.4426950408889634f}, l[2] = {1.0f, 1.0f};
;     const int tlo = metaq ? 0 : (qs - 4 > 0 ? qs - 4 : 0), thi = metaq ? -1 : qs;
;     const bf16_t* kbase = z + zlaneRC(c, 2048 + kvh * 64 + 8 * h);
;     const bf16_t* vbase = z + zlaneRC(lane & 15, 2304 + kvh * 64 + 8 * (lane >> 4));
;     bf16x8 kf[4]; u32x4 vv[4];
;     int t = -1;
;     { const size_t ro = zrowU(SEQ, 18);
; #pragma unroll
;       for (int s = 0; s < 4; ++s) kf[s] = *(const bf16x8*)(kbase + ro + (((s >> 1) << 9) | ((s & 1) << 8)));
; #pragma unroll
;       for (int i = 0; i < 4; ++i) vv[i] = *(const u32x4*)(vbase + ro + (((i >> 1) << 13) | ((i & 1) << 9))); }
.LBB0_196:
	s_lshr_b32 s0, s4, 8
	s_mul_i32 s78, s0, 18
	s_lshl_b32 s0, s4, 8
	s_lshl_b32 s1, s4, 9
	s_and_b32 s0, s0, 0x8000
	s_and_b32 s1, s1, 0x4000
	s_or_b32 s0, s0, s1
	s_lshl_b32 s1, s4, 5
	s_and_b32 s1, s1, 0x800
	s_or_b32 s4, s0, s1
	s_lshl_b64 s[0:1], s[78:79], 17
	s_add_u32 s0, s82, s0
	s_addc_u32 s1, s83, s1
	s_lshl_b32 s4, s4, 1
	v_ashrrev_i32_e32 v126, 5, v2
	s_add_u32 s0, s0, s4
	s_addc_u32 s1, s1, 0
	s_lshl_b32 s27, s22, 7
	v_lshlrev_b32_e32 v3, 3, v126
	v_add_u32_e32 v20, s27, v3
	v_lshlrev_b32_e32 v0, 9, v127
	v_lshlrev_b32_e32 v4, 3, v127
	s_movk_i32 s4, 0x2078
	v_bitop3_b32 v124, v4, s4, v0 bitop3:0xc8
	v_lshlrev_b32_e32 v4, 5, v20
	v_lshlrev_b32_e32 v0, 8, v20
	v_and_b32_e32 v4, 0x1000, v4
	v_lshlrev_b32_e32 v5, 7, v126
	s_movk_i32 s4, 0x780
	v_and_b32_e32 v0, 0xffff0000, v0
	v_and_or_b32 v4, v5, s4, v4
	v_or3_b32 v0, v4, v0, v124
	v_lshl_add_u64 v[16:17], v[0:1], 1, s[0:1]
	v_add_u32_e32 v0, 64, v20
	v_lshlrev_b32_e32 v20, 8, v0
	v_and_b32_e32 v20, 0xffff0000, v20
	v_lshlrev_b32_e32 v21, 5, v0
	v_lshlrev_b32_e32 v0, 4, v0
	s_lshl_b32 s4, s22, 1
	v_and_b32_e32 v0, 0x780, v0
	v_and_or_b32 v20, v21, s62, v20
	s_ashr_i32 s5, s4, 31
	v_or3_b32 v0, v20, v0, v124
	s_lshl_b64 s[4:5], s[4:5], 2
	v_lshl_add_u64 v[32:33], v[0:1], 1, s[0:1]
	s_add_u32 s4, s24, s4
	global_load_dwordx4 v[4:7], v[16:17], off
	global_load_dwordx4 v[8:11], v[16:17], off offset:512
	global_load_dwordx4 v[12:15], v[16:17], off offset:1024
	s_nop 0
	global_load_dwordx4 v[16:19], v[16:17], off offset:1536
	s_nop 0
	global_load_dwordx4 v[20:23], v[32:33], off
	global_load_dwordx4 v[24:27], v[32:33], off offset:512
	global_load_dwordx4 v[28:31], v[32:33], off offset:1024
	s_nop 0
	global_load_dwordx4 v[32:35], v[32:33], off offset:1536
	s_waitcnt lgkmcnt(0)
	s_addc_u32 s5, s25, s5
	global_load_dwordx2 v[36:37], v1, s[4:5]
	s_lshl_b32 s4, s22, 4
	s_andn2_b32 s4, s4, 63
	v_lshlrev_b32_e32 v125, 2, v126
	v_bfe_u32 v0, v2, 2, 2
	s_add_i32 s5, s4, 0x800
	v_or_b32_e32 v41, v125, v0
	v_add_u32_e32 v0, s5, v3
	v_lshlrev_b32_e32 v38, 5, v0
	v_lshlrev_b32_e32 v3, 8, v0
	v_and_b32_e32 v38, 0x1000, v38
	v_lshlrev_b32_e32 v0, 4, v0
	v_and_b32_e32 v0, 0x780, v0
	v_and_or_b32 v3, v3, s12, v38
	v_or3_b32 v0, v3, v0, v124
	v_lshl_add_u64 v[114:115], v[0:1], 1, s[82:83]
	v_ashrrev_i32_e32 v0, 1, v2
	s_addk_i32 s4, 0x900
	v_and_b32_e32 v3, -8, v0
	v_and_b32_e32 v40, 15, v2
	v_add_u32_e32 v0, s4, v3
	v_lshlrev_b32_e32 v38, 8, v0
	v_lshlrev_b32_e32 v39, 5, v0
	v_lshlrev_b32_e32 v0, 4, v0
	v_lshlrev_b32_e32 v44, 3, v40
	v_and_b32_e32 v39, 0x1000, v39
	v_and_b32_e32 v0, 0x780, v0
	v_and_or_b32 v38, v38, s12, v44
	s_mov_b32 s4, 0x9000000
	v_or3_b32 v0, v38, v39, v0
	v_add_co_u32_e32 v38, vcc, s4, v114
	v_lshl_add_u64 v[116:117], v[0:1], 1, s[82:83]
	s_nop 0
	v_addc_co_u32_e32 v39, vcc, 0, v115, vcc
	global_load_dwordx4 v[94:97], v[38:39], off
	global_load_dwordx4 v[90:93], v[38:39], off offset:512
	global_load_dwordx4 v[86:89], v[38:39], off offset:1024
	global_load_dwordx4 v[82:85], v[38:39], off offset:1536
	v_add_co_u32_e32 v38, vcc, s4, v116
	s_mov_b32 s4, 0x9004000
	s_nop 0
	v_addc_co_u32_e32 v39, vcc, 0, v117, vcc
	global_load_dwordx4 v[98:101], v[38:39], off
	global_load_dwordx4 v[102:105], v[38:39], off offset:1024
	v_add_co_u32_e32 v38, vcc, s4, v116
	v_sub_u32_e64 v0, s28, 4 clamp
	s_nop 0
	v_addc_co_u32_e32 v39, vcc, 0, v117, vcc
	global_load_dwordx4 v[106:109], v[38:39], off
	global_load_dwordx4 v[110:113], v[38:39], off offset:1024
	s_and_b64 s[4:5], s[68:69], exec
	v_lshlrev_b32_e32 v42, 2, v2
	v_and_b32_e32 v43, 16, v2
	v_lshl_add_u32 v129, v2, 4, s23
	v_readfirstlane_b32 s4, v0
	v_lshlrev_b32_e32 v2, 3, v2
	s_cselect_b32 s78, 0, s4
	v_lshlrev_b32_e32 v0, 1, v43
	v_and_b32_e32 v2, 24, v2
	s_movk_i32 s4, 0xc0
	s_waitcnt vmcnt(16)
	ds_write_b128 v129, v[4:7] offset:6144
	s_waitcnt vmcnt(15)
	ds_write_b128 v129, v[8:11] offset:7168
	s_waitcnt vmcnt(14)
	ds_write_b128 v129, v[12:15] offset:8192
	s_waitcnt vmcnt(13)
	ds_write_b128 v129, v[16:19] offset:9216
	s_waitcnt vmcnt(12)
	ds_write_b128 v129, v[20:23] offset:10240
	s_waitcnt vmcnt(11)
	ds_write_b128 v129, v[24:27] offset:11264
	s_waitcnt vmcnt(10)
	ds_write_b128 v129, v[28:31] offset:12288
	s_waitcnt vmcnt(9)
	ds_write_b128 v129, v[32:35] offset:13312
	v_add3_u32 v16, s23, v0, v2
	v_mul_lo_u32 v17, v41, s4
	s_mul_i32 s4, s22, 0x408
	v_mul_u32_u24_e32 v0, 0xc0, v40
	v_lshlrev_b32_e32 v2, 1, v3
	v_mov_b32_e32 v14, v1
	v_mov_b32_e32 v15, v1
	s_waitcnt vmcnt(8)
	v_pk_mul_f32 v[118:119], v[36:37], s[66:67] op_sel_hi:[1,0]
	v_xor_b32_e32 v145, 0x80, v42
	s_add_i32 s87, s4, 0
	v_add3_u32 v164, s23, v0, v2
	v_mov_b32_e32 v0, v1
	v_mov_b32_e32 v2, v1
	v_mov_b32_e32 v3, v1
	v_mov_b32_e32 v4, v1
	v_mov_b32_e32 v5, v1
	v_mov_b32_e32 v6, v1
	v_mov_b32_e32 v7, v1
	v_mov_b32_e32 v8, v1
	v_mov_b32_e32 v9, v1
	v_mov_b32_e32 v10, v1
	v_mov_b32_e32 v11, v1
	v_mov_b32_e32 v12, v1
	v_mov_b32_e32 v13, v1
	v_mov_b64_e32 v[64:65], v[14:15]
	v_mov_b64_e32 v[48:49], v[14:15]
	v_mov_b64_e32 v[32:33], v[14:15]
	s_add_i32 s87, s87, 0x1c000
	v_add_u32_e32 v165, v16, v17
	v_mov_b64_e32 v[62:63], v[12:13]
	v_mov_b64_e32 v[60:61], v[10:11]
	v_mov_b64_e32 v[58:59], v[8:9]
	v_mov_b64_e32 v[56:57], v[6:7]
	v_mov_b64_e32 v[54:55], v[4:5]
	v_mov_b64_e32 v[52:53], v[2:3]
	v_mov_b64_e32 v[50:51], v[0:1]
	v_mov_b64_e32 v[46:47], v[12:13]
	v_mov_b64_e32 v[44:45], v[10:11]
	v_mov_b64_e32 v[42:43], v[8:9]
	v_mov_b64_e32 v[40:41], v[6:7]
	v_mov_b64_e32 v[38:39], v[4:5]
	v_mov_b64_e32 v[36:37], v[2:3]
	v_mov_b64_e32 v[34:35], v[0:1]
	v_mov_b64_e32 v[30:31], v[12:13]
	v_mov_b64_e32 v[28:29], v[10:11]
	v_mov_b64_e32 v[26:27], v[8:9]
	v_mov_b64_e32 v[24:25], v[6:7]
	v_mov_b64_e32 v[22:23], v[4:5]
	v_mov_b64_e32 v[20:21], v[2:3]
	v_mov_b64_e32 v[18:19], v[0:1]
	v_mov_b64_e32 v[16:17], v[14:15]
	s_add_i32 s86, s28, -4
	v_or_b32_e32 v130, 1, v125
	v_or_b32_e32 v131, 2, v125
	v_or_b32_e32 v132, 3, v125
	v_add_u32_e32 v133, 8, v125
	v_add_u32_e32 v134, 9, v125
	v_add_u32_e32 v135, 10, v125
	v_add_u32_e32 v136, 11, v125
	v_add_u32_e32 v137, 16, v125
	v_add_u32_e32 v138, 17, v125
	v_add_u32_e32 v139, 18, v125
	v_add_u32_e32 v140, 19, v125
	v_add_u32_e32 v141, 24, v125
	v_add_u32_e32 v142, 25, v125
	v_add_u32_e32 v143, 26, v125
	v_add_u32_e32 v144, 27, v125
	v_add_u32_e32 v146, -3, v128
	v_add_u32_e32 v147, -8, v128
	v_add_u32_e32 v148, -9, v128
	v_add_u32_e32 v149, -10, v128
	v_add_u32_e32 v150, -11, v128
	v_add_u32_e32 v151, -16, v128
	v_subrev_u32_e32 v152, 17, v128
	v_subrev_u32_e32 v153, 18, v128
	v_subrev_u32_e32 v158, 19, v128
	v_subrev_u32_e32 v159, 24, v128
	v_subrev_u32_e32 v160, 25, v128
	v_subrev_u32_e32 v161, 26, v128
	v_subrev_u32_e32 v162, 27, v128
	v_lshl_add_u32 v163, v128, 2, s87
	s_mov_b32 s31, -1
	v_mov_b32_e32 v167, 1.0
	v_mov_b32_e32 v166, 1.0
	v_mov_b64_e32 v[14:15], v[12:13]
	v_mov_b64_e32 v[12:13], v[10:11]
	v_mov_b64_e32 v[10:11], v[8:9]
	v_mov_b64_e32 v[8:9], v[6:7]
	v_mov_b64_e32 v[6:7], v[4:5]
	v_mov_b64_e32 v[4:5], v[2:3]
	v_mov_b64_e32 v[2:3], v[0:1]
	.p2align 6
